# K-start rotation (32 starts) also in phase 13 GEMM loop
# baseline (speedup 1.0000x reference)
;     __device__ __forceinline__ bool next(int i, Unit& u) const { if (i != 0 || c >= n) return false; u.pm = 0; u.pn = c; u.kt0 = 0; u.nkt = ntk; u.piece = -1; return true; }
; #define PG8_WAIT_V(n) asm volatile("s_waitcnt vmcnt(" #n ")" ::: "memory")
; #define PG8_BAR __builtin_amdgcn_s_barrier()
; template <class Epi, class Sched>
; __device__ __forceinline__ void gemm_phase(LAS unsigned char* lds, const Gemm g, const Sched& S, const Epi& E) {
;     const int tid = threadIdx.x, wid = __builtin_amdgcn_readfirstlane(tid >> 6), lane = tid & 63, wr = wid >> 2, wc = wid & 3, fr = lane & 15, fq = lane >> 4;
;     unsigned voffA[2], voffB[2];
; #pragma unroll
;     for (int i = 0; i < 2; ++i) { int R, C; stage_rc(tid * 16 + i * 8192, R, C); const int Rb = Epi::PERM ? ((R & ~31) + perm32(R & 31)) : R;
;         voffA[i] = (unsigned)(R * g.lda + C) * 2u; voffB[i] = (unsigned)(Rb * g.ldb + C) * 2u; }
;     const size_t kstep = (size_t)(BK * 2);
;     const size_t hstepA = g.a_half ? g.a_half : (size_t)HALF * g.lda * 2, hstepB = g.b_half ? g.b_half : (size_t)HALF * g.ldb * 2;
;     const size_t tstepA = g.a_tile ? g.a_tile : (size_t)BM * g.lda * 2, tstepB = g.b_tile ? g.b_tile : (size_t)BM * g.ldb * 2;
;     const unsigned ldsw = (unsigned)wid * 1024u;
;     const int aoff = lds_byte(wr * 64 + fr, fq * 8), boff = lds_byte(wc * 32 + fr, fq * 8);
;     ...
;     Unit cur, nxt; int ui = 0;
;     if (!S.next(0, cur)) return;
;     f32x4 acc[2][2][4][2];
; #pragma unroll
;     for (int a = 0; a < 2; ++a)
; #pragma unroll
;         for (int b = 0; b < 2; ++b)
; #pragma unroll
;             for (int m = 0; m < 4; ++m)
; #pragma unroll
;                 for (int n = 0; n < 2; ++n) acc[a][b][m][n] = (f32x4){0.f, 0.f, 0.f, 0.f};
;     bf16x8 At[4][2], B0[2][2], B1[2][2];
;     const char* cA = (const char*)g.A + (size_t)cur.pm * tstepA + (size_t)cur.pn * g.a_pn_off + (size_t)cur.kt0 * kstep; const char* cB = (const char*)g.Bt + (size_t)cur.pn * tstepB + (size_t)cur.kt0 * kstep;
;     PG8_STAGE(PG8_SB(0, 0), cB, voffB); PG8_STAGE(PG8_SA(0, 0), cA, voffA); PG8_STAGE(PG8_SB(0, 1), cB + hstepB, voffB); PG8_STAGE(PG8_SA(0, 1), cA + hstepA, voffA);
;     if (wr == 1) PG8_BAR;
;     PG8_WAIT_V(4); PG8_BAR;
;     PG8_STAGE(PG8_SB(1, 0), cB + kstep, voffB); PG8_STAGE(PG8_SA(1, 0), cA + kstep, voffA); PG8_STAGE(PG8_SB(1, 1), cB + hstepB + kstep, voffB);
;     PG8_WAIT_V(6); PG8_BAR;
.LBB0_1902:
	s_cmp_lt_i32 s86, 14
	s_cselect_b64 s[4:5], -1, 0
	s_and_b64 s[6:7], s[4:5], s[6:7]
	s_andn2_b64 vcc, exec, s[6:7]
	s_cbranch_vccnz .LBB0_1955
	s_cmpk_gt_i32 s2, 0x1af
	v_readfirstlane_b32 s3, v160
	s_cbranch_scc1 .LBB0_1955
	s_max_i32 s6, s2, 0x100
	s_addk_i32 s6, 0xff00
	s_mul_hi_u32 s9, s6, 0xba2e8ba3
	s_lshr_b32 s7, s9, 3
	s_mul_i32 s8, s7, -11
	s_add_i32 s8, s8, s6
	s_lshl_b32 s6, s8, 3
	s_ashr_i32 s7, s6, 31
	s_lshl_b64 s[6:7], s[6:7], 7
	s_cmpk_lt_i32 s2, 0x100
	s_cselect_b64 s[10:11], -1, 0
	s_and_b64 s[10:11], s[10:11], exec
	s_cselect_b32 s10, s2, 0
	s_cselect_b32 s11, 0, s6
	s_cselect_b32 s12, 0, s7
	s_ashr_i32 s6, s10, 31
	s_lshr_b32 s6, s6, 29
	s_add_i32 s6, s10, s6
	s_ashr_i32 s6, s6, 3
	s_mulk_i32 s6, 0xff01
	s_lshl_b32 s7, s10, 5
	s_add_i32 s6, s6, s7
	s_ashr_i32 s7, s6, 31
	s_lshr_b32 s7, s7, 26
	s_add_i32 s10, s6, s7
	s_and_b32 s7, s10, 0xffffffc0
	s_sub_i32 s13, s6, s7
	s_bfe_i32 s6, s13, 0x80000
	s_bfe_u32 s6, s6, 0x3000c
	s_add_i32 s14, s13, s6
	s_bfe_i32 s6, s14, 0x80000
	s_sext_i32_i16 s6, s6
	s_ashr_i32 s15, s6, 3
	s_bfe_u32 s16, s9, 0x30003
	s_cmpk_lt_i32 s2, 0x100
	s_cselect_b64 s[6:7], -1, 0
	s_and_b64 s[6:7], s[6:7], exec
	s_cselect_b32 s64, s15, s16
	s_and_b32 s7, s14, 0xf8
	s_ashr_i32 s6, s10, 6
	s_sub_i32 s7, s13, s7
	s_lshl_b32 s6, s6, 3
	s_sext_i32_i8 s7, s7
	s_add_i32 s10, s6, s7
	s_lshr_b32 s6, s9, 6
	s_add_i32 s9, s6, 32
	s_cmpk_lt_i32 s2, 0x100
	s_cselect_b64 s[16:17], -1, 0
	s_and_b64 s[6:7], s[16:17], exec
	s_cselect_b32 s65, s10, s9
	s_add_u32 s30, s84, 0x11d39000
	s_waitcnt vmcnt(0)
	v_lshlrev_b32_e32 v0, 4, v160
	v_and_b32_e32 v1, 32, v160
	s_addc_u32 s31, s85, 0
	v_bfe_u32 v2, v160, 2, 4
	v_bitop3_b32 v8, v0, v1, 48 bitop3:0x6c
	v_lshrrev_b32_e32 v3, 3, v160
	s_movk_i32 s6, 0x70
	v_add_u32_e32 v0, 0x2000, v0
	s_add_u32 s34, s84, 0x5100000
	v_and_or_b32 v3, v3, s6, v2
	v_lshrrev_b32_e32 v0, 7, v0
	s_movk_i32 s6, 0xf0
	s_addc_u32 s35, s85, 0
	v_and_or_b32 v0, v0, s6, v2
	s_lshr_b32 s18, s3, 6
	s_mul_i32 s6, s64, 0x2c0000
	s_lshr_b32 s19, s3, 8
	s_lshl_b32 s36, s18, 10
	s_ashr_i32 s7, s6, 31
	s_add_u32 s6, s34, s6
	s_addc_u32 s7, s35, s7
	s_mul_i32 s10, s65, 0x2c0000
	v_and_b32_e32 v9, 64, v160
	s_mul_hi_i32 s9, s65, 0x2c0000
	s_add_u32 s10, s30, s10
	v_or_b32_e32 v1, v8, v9
	s_addc_u32 s9, s31, s9
	v_lshrrev_b32_e32 v1, 1, v1
	v_mul_u32_u24_e32 v10, 0x1600, v3
	s_add_u32 s24, s6, s11
	v_or_b32_e32 v3, v1, v10
	s_addc_u32 s25, s7, s12
	s_bfe_u32 s72, s2, 0x50003
	s_lshl_b32 s72, s72, 8
	s_cmpk_lt_u32 s2, 0x100
	s_cselect_b32 s72, s72, 0
	s_add_u32 s24, s24, s72
	s_addc_u32 s25, s25, 0
	s_add_i32 s37, s36, 0
	v_lshlrev_b32_e32 v128, 1, v3
	v_mul_u32_u24_e32 v11, 0x1600, v0
	s_add_i32 m0, s37, 0x10000
	v_or_b32_e32 v0, v11, v1
	global_load_lds_dwordx4 v128, s[24:25]
	s_add_i32 m0, s37, 0x12000
	v_lshlrev_b32_e32 v130, 1, v0
	s_add_u32 s6, s10, s11
	global_load_lds_dwordx4 v130, s[24:25]
	s_addc_u32 s7, s9, s12
	s_add_u32 s6, s6, s72
	s_addc_u32 s7, s7, 0
	s_mov_b32 m0, s37
	s_add_i32 s38, s37, 0x2000
	global_load_lds_dwordx4 v128, s[6:7]
	s_mov_b32 m0, s38
	s_add_u32 s10, s24, 0x160000
	global_load_lds_dwordx4 v130, s[6:7]
	s_addc_u32 s11, s25, 0
	s_add_i32 m0, s37, 0x14000
	v_mov_b32_e32 v133, 0
	global_load_lds_dwordx4 v128, s[10:11]
	s_add_i32 m0, s37, 0x16000
	v_mov_b32_e32 v129, v133
	global_load_lds_dwordx4 v130, s[10:11]
	s_add_u32 s10, s6, 0x160000
	s_addc_u32 s11, s7, 0
	s_add_i32 s39, s37, 0x4000
	s_mov_b32 m0, s39
	s_add_i32 s40, s37, 0x6000
	global_load_lds_dwordx4 v128, s[10:11]
	s_mov_b32 m0, s40
	v_mov_b32_e32 v131, v133
	global_load_lds_dwordx4 v130, s[10:11]
	s_load_dwordx2 s[10:11], s[0:1], 0xc0
	s_mov_b32 s9, 0
	s_movk_i32 s41, 0x2000
	v_lshl_add_u64 v[6:7], s[24:25], 0, v[128:129]
	v_lshl_add_u64 v[4:5], s[24:25], 0, v[130:131]
	v_lshl_add_u64 v[2:3], s[6:7], 0, v[128:129]
	s_cmp_lg_u32 s19, 1
	v_lshl_add_u64 v[0:1], s[6:7], 0, v[130:131]
	s_cbranch_scc1 .LBB0_1906
	s_barrier
.LBB0_1906:
	s_waitcnt lgkmcnt(0)
	s_add_u32 s12, s10, 0x4000000
	s_addc_u32 s13, s11, 0
	s_add_u32 s14, s84, 0x788a000
	s_addc_u32 s15, s85, 0
	s_add_u32 s42, s84, 0x17ab9000
	s_addc_u32 s43, s85, 0
	s_lshl_b32 s18, s18, 5
	s_and_b32 s21, s18, 0x60
	s_lshl_b32 s44, s19, 6
	s_lshl_b32 s20, s19, 13
	s_lshl_b32 s22, s21, 7
	s_and_b64 s[16:17], s[16:17], exec
	s_mov_b64 s[16:17], 0x80
	s_cselect_b32 s66, 0x58, 8
	s_cselect_b32 s8, -1, s8
	s_add_i32 m0, s37, 0x18000
	v_lshl_add_u64 v[6:7], v[6:7], 0, s[16:17]
	s_waitcnt vmcnt(4)
	s_barrier
	global_load_lds_dwordx4 v[6:7], off
	v_lshl_add_u64 v[4:5], v[4:5], 0, s[16:17]
	s_add_i32 m0, s37, 0x1a000
	s_add_i32 s45, s37, 0x8000
	s_add_i32 s46, s37, 0xa000
	global_load_lds_dwordx4 v[4:5], off
	v_lshl_add_u64 v[2:3], v[2:3], 0, s[16:17]
	s_mov_b32 m0, s45
	s_add_u32 s18, s24, 0x160080
	global_load_lds_dwordx4 v[2:3], off
	v_lshl_add_u64 v[0:1], v[0:1], 0, s[16:17]
	s_mov_b32 m0, s46
	s_addc_u32 s19, s25, 0
	global_load_lds_dwordx4 v[0:1], off
	s_add_i32 m0, s37, 0x1c000
	v_lshl_add_u64 v[0:1], s[18:19], 0, v[128:129]
	global_load_lds_dwordx4 v[0:1], off
	v_lshl_add_u64 v[0:1], s[18:19], 0, v[130:131]
	s_add_i32 m0, s37, 0x1e000
	v_and_b32_e32 v152, 15, v160
	global_load_lds_dwordx4 v[0:1], off
	v_bfe_u32 v0, v160, 4, 2
	v_lshlrev_b32_e32 v1, 4, v0
	v_lshlrev_b32_e32 v2, 6, v160
	s_movk_i32 s18, 0x3c0
	v_and_or_b32 v2, v2, s18, v1
	v_and_b32_e32 v3, 32, v184
	v_lshl_or_b32 v1, v152, 6, v1
	s_waitcnt vmcnt(6)
	v_lshl_or_b32 v154, v0, 2, s21
	v_add_u16_e32 v0, v8, v9
	v_bitop3_b32 v1, v1, s20, v3 bitop3:0xde
	v_bitop3_b32 v153, s22, v2, v3 bitop3:0xf6
	v_lshrrev_b16_e32 v0, 1, v0
	s_add_i32 s47, 0, 0x10000
	s_add_i32 s49, 0, 0x14000
	v_add_lshl_u32 v134, v10, v0, 1
	v_mov_b32_e32 v135, v133
	v_add_lshl_u32 v136, v11, v0, 1
	v_mov_b32_e32 v137, v133
	v_add_u32_e32 v155, s47, v153
	v_add_u32_e32 v156, 0, v1
	s_mov_b32 s48, 0xc000
	v_add_u32_e32 v157, s49, v153
	s_movk_i32 s50, 0x1fff
	s_movk_i32 s51, 0x1f80
	s_movk_i32 s52, 0x1f7f
	s_movk_i32 s53, 0x1f70
	s_movk_i32 s54, 0x1f6f
	s_movk_i32 s55, 0x1f60
	s_movk_i32 s56, 0x1f5f
	s_movk_i32 s57, 0x1f50
	s_movk_i32 s58, 0x1f4f
	s_mov_b32 s59, s9
	s_sub_u32 s24, s24, s72
	s_subb_u32 s25, s25, 0
	s_sub_u32 s6, s6, s72
	s_subb_u32 s7, s7, 0
	s_barrier
	s_branch .LBB0_1908

.LBB0_1908:
	s_mov_b32 s73, s72
	s_add_i32 s59, s59, 1
	s_mul_i32 s18, s59, s96
	s_add_i32 s18, s18, s2
	s_bfe_u32 s72, s18, 0x50003
	s_lshl_b32 s72, s72, 8
	s_cmpk_lt_u32 s18, 0x100
	s_cselect_b32 s72, s72, 0
	s_cmpk_lt_i32 s18, 0x100
	s_cselect_b64 s[22:23], -1, 0
	s_max_i32 s19, s18, 0x100
	s_addk_i32 s19, 0xff00
	s_mul_hi_u32 s20, s19, 0xba2e8ba3
	s_lshr_b32 s63, s20, 3
	s_mov_b64 s[26:27], 0
	s_and_b64 vcc, exec, s[22:23]
	s_movk_i32 s61, 0x58
	s_mov_b32 s60, -1
	s_cbranch_vccnz .LBB0_1910
	s_mul_i32 s20, s63, -11
	s_add_i32 s60, s20, s19
	s_lshl_b32 s20, s60, 3
	s_ashr_i32 s21, s20, 31
	s_lshl_b64 s[26:27], s[20:21], 7
	s_mov_b32 s61, 8

; #define PG8_STAGE(bufoff, gbase, voff) do { _Pragma("unroll") for (int _i = 0; _i < 2; ++_i) \
;         __builtin_amdgcn_global_load_lds((const unsigned*)((const char*)(gbase) + (voff)[_i]), (LAS unsigned*)(lds + (bufoff) + ldsw + _i * 8192), 16, 0, 0); } while (0)
; #define PG8_LDA(dst, b, h) do { _Pragma("unroll") for (int m = 0; m < 4; ++m) _Pragma("unroll") for (int k = 0; k < 2; ++k) dst[m][k] = *(const LAS bf16x8*)(lds + PG8_SA(b, h) + aoff + m * 2048 + k * 1024); } while (0)
; #define PG8_LDB(dst, b, h) do { _Pragma("unroll") for (int n = 0; n < 2; ++n) _Pragma("unroll") for (int k = 0; k < 2; ++k) dst[n][k] = *(const LAS bf16x8*)(lds + PG8_SB(b, h) + boff + n * 2048 + k * 1024); } while (0)
; #define PG8_MMA(ai, bj, At, Bt) do { __builtin_amdgcn_s_setprio(1); _Pragma("unroll") for (int m = 0; m < 4; ++m) _Pragma("unroll") for (int n = 0; n < 2; ++n) _Pragma("unroll") for (int k = 0; k < 2; ++k) \
;         acc[ai][bj][m][n] = __builtin_amdgcn_mfma_f32_16x16x32_bf16(Bt[n][k], At[m][k], acc[ai][bj][m][n], 0, 0, 0); __builtin_amdgcn_s_setprio(0); } while (0)
; #define PG8_WAIT_V(n) asm volatile("s_waitcnt vmcnt(" #n ")" ::: "memory")
; #define PG8_BAR __builtin_amdgcn_s_barrier()
; template <class Epi, class Sched>
; __device__ __forceinline__ void gemm_phase(LAS unsigned char* lds, const Gemm g, const Sched& S, const Epi& E) {
;     ...
;         for (int t = 0; t < nt; t += 2) {
;             const bool last = (t == nt - 2);
;             const char* a1 = cA + (size_t)(t + 1) * kstep;
;             const char* a2 = last ? nA : cA + (size_t)(t + 2) * kstep; const char* b2 = last ? nB : cB + (size_t)(t + 2) * kstep;
;             const char* a3 = a2 + kstep; const char* b3 = b2 + kstep;
;             PG8_LDB(B0, 0, 0); PG8_SCHED; PG8_LDA(At, 0, 0); PG8_STAGE(PG8_SA(1, 1), a1 + hstepA, voffA);
;             PG8_WAIT_L(8); PG8_BAR; PG8_WAIT_L(0); PG8_MMA(0, 0, At, B0); PG8_BAR; PG8_SCHED;
;             PG8_LDB(B1, 0, 1); PG8_STAGE(PG8_SB(0, 0), b2, voffB);
;             PG8_BAR; PG8_WAIT_L(0); if constexpr (!Epi::DIAG) PG8_MMA(0, 1, At, B1); PG8_BAR;
;             PG8_LDA(At, 0, 1); PG8_STAGE(PG8_SA(0, 0), a2, voffA);
;             PG8_BAR; PG8_WAIT_L(0); if constexpr (!Epi::DIAG) PG8_MMA(1, 0, At, B0); PG8_BAR; PG8_SCHED;
;             PG8_STAGE(PG8_SB(0, 1), b2 + hstepB, voffB);
;             PG8_WAIT_V(6); PG8_BAR; PG8_MMA(1, 1, At, B1); PG8_BAR;
.LBB0_1915:
	ds_read_b128 v[138:141], v155
	ds_read_b128 v[142:145], v155 offset:1024
	ds_read_b128 v[146:149], v155 offset:2048
	ds_read_b128 v[162:165], v155 offset:3072
	s_add_i32 s68, s24, 2
	s_add_u32 s74, s73, 0x100
	s_cmp_eq_u32 s74, 0x2c00
	s_cselect_b32 s74, 0, s74
	s_add_u32 s25, s6, s74
	s_addc_u32 s26, s7, 0
	s_sub_u32 s25, s25, 0x160080
	s_subb_u32 s26, s26, 0
	s_add_u32 s76, s20, s72
	s_addc_u32 s77, s21, 0
	s_cmp_eq_u32 s28, s24
	s_cselect_b32 s27, s77, s26
	s_cselect_b32 s26, s76, s25
	s_add_u32 s76, s29, s74
	s_addc_u32 s77, s67, 0
	s_sub_u32 s76, s76, 0x100
	s_subb_u32 s77, s77, 0
	s_add_u32 s78, s22, s72
	s_addc_u32 s79, s23, 0
	s_cmp_eq_u32 s28, s24
	s_cselect_b32 s25, s79, s77
	s_cselect_b32 s24, s78, s76
	s_add_u32 s76, s6, s73
	s_addc_u32 s77, s7, 0
	v_lshl_add_u64 v[150:151], s[76:77], 0, v[134:135]
	s_add_i32 m0, s37, 0xc000
	ds_read_b128 v[166:169], v156
	ds_read_b128 v[170:173], v156 offset:1024
	ds_read_b128 v[174:177], v156 offset:2048
	ds_read_b128 v[178:181], v156 offset:3072
	ds_read_b128 v[186:189], v156 offset:4096
	ds_read_b128 v[190:193], v156 offset:5120
	ds_read_b128 v[194:197], v156 offset:6144
	ds_read_b128 v[198:201], v156 offset:7168
	global_load_lds_dwordx4 v[150:151], off
	v_lshl_add_u64 v[150:151], s[76:77], 0, v[136:137]
	s_add_i32 m0, s37, 0xe000
	s_nop 0
	global_load_lds_dwordx4 v[150:151], off
	s_waitcnt lgkmcnt(8)
	s_barrier
	s_waitcnt lgkmcnt(0)
	s_setprio 1
	s_waitcnt lgkmcnt(0)
	v_mfma_f32_16x16x32_bf16 v[124:127], v[138:141], v[166:169], v[124:127]
	v_mfma_f32_16x16x32_bf16 v[120:123], v[146:149], v[166:169], v[120:123]
	v_mfma_f32_16x16x32_bf16 v[116:119], v[138:141], v[174:177], v[116:119]
	v_mfma_f32_16x16x32_bf16 v[112:115], v[146:149], v[174:177], v[112:115]
	v_mfma_f32_16x16x32_bf16 v[104:107], v[138:141], v[186:189], v[104:107]
	v_mfma_f32_16x16x32_bf16 v[96:99], v[146:149], v[186:189], v[96:99]
	v_mfma_f32_16x16x32_bf16 v[88:91], v[138:141], v[194:197], v[88:91]
	v_mfma_f32_16x16x32_bf16 v[80:83], v[146:149], v[194:197], v[80:83]
	v_mfma_f32_16x16x32_bf16 v[124:127], v[142:145], v[170:173], v[124:127]
	v_mfma_f32_16x16x32_bf16 v[120:123], v[162:165], v[170:173], v[120:123]
	v_mfma_f32_16x16x32_bf16 v[116:119], v[142:145], v[178:181], v[116:119]
	v_mfma_f32_16x16x32_bf16 v[112:115], v[162:165], v[178:181], v[112:115]
	v_mfma_f32_16x16x32_bf16 v[104:107], v[142:145], v[190:193], v[104:107]
	v_mfma_f32_16x16x32_bf16 v[96:99], v[162:165], v[190:193], v[96:99]
	v_mfma_f32_16x16x32_bf16 v[88:91], v[142:145], v[198:201], v[88:91]
	v_mfma_f32_16x16x32_bf16 v[80:83], v[162:165], v[198:201], v[80:83]
	s_setprio 0
	s_barrier
	s_add_i32 s69, s47, s36
	v_lshl_add_u64 v[150:151], s[24:25], 0, v[128:129]
	s_mov_b32 m0, s69
	ds_read_b128 v[202:205], v157
	ds_read_b128 v[206:209], v157 offset:1024
	ds_read_b128 v[210:213], v157 offset:2048
	ds_read_b128 v[214:217], v157 offset:3072
	global_load_lds_dwordx4 v[150:151], off
	v_lshl_add_u64 v[158:159], s[24:25], 0, v[130:131]
	s_add_i32 m0, s69, 0x2000
	s_nop 0
	global_load_lds_dwordx4 v[158:159], off
	s_barrier
	s_waitcnt lgkmcnt(0)
	s_setprio 1
	s_waitcnt lgkmcnt(0)
	v_mfma_f32_16x16x32_bf16 v[108:111], v[202:205], v[166:169], v[108:111]
	v_mfma_f32_16x16x32_bf16 v[100:103], v[210:213], v[166:169], v[100:103]
	v_mfma_f32_16x16x32_bf16 v[92:95], v[202:205], v[174:177], v[92:95]
	v_mfma_f32_16x16x32_bf16 v[84:87], v[210:213], v[174:177], v[84:87]
	v_mfma_f32_16x16x32_bf16 v[76:79], v[202:205], v[186:189], v[76:79]
	v_mfma_f32_16x16x32_bf16 v[72:75], v[210:213], v[186:189], v[72:75]
	v_mfma_f32_16x16x32_bf16 v[68:71], v[202:205], v[194:197], v[68:71]
	v_mfma_f32_16x16x32_bf16 v[64:67], v[210:213], v[194:197], v[64:67]
	v_mfma_f32_16x16x32_bf16 v[108:111], v[206:209], v[170:173], v[108:111]
	v_mfma_f32_16x16x32_bf16 v[100:103], v[214:217], v[170:173], v[100:103]
	v_mfma_f32_16x16x32_bf16 v[92:95], v[206:209], v[178:181], v[92:95]
	v_mfma_f32_16x16x32_bf16 v[84:87], v[214:217], v[178:181], v[84:87]
	v_mfma_f32_16x16x32_bf16 v[76:79], v[206:209], v[190:193], v[76:79]
	v_mfma_f32_16x16x32_bf16 v[72:75], v[214:217], v[190:193], v[72:75]
	v_mfma_f32_16x16x32_bf16 v[68:71], v[206:209], v[198:201], v[68:71]
	v_mfma_f32_16x16x32_bf16 v[64:67], v[214:217], v[198:201], v[64:67]
	s_setprio 0
	s_mov_b32 m0, s37
	v_lshl_add_u64 v[182:183], s[26:27], 0, v[128:129]
	s_barrier
	ds_read_b128 v[166:169], v156 offset:16384
	ds_read_b128 v[170:173], v156 offset:17408
	ds_read_b128 v[174:177], v156 offset:18432
	ds_read_b128 v[178:181], v156 offset:19456
	ds_read_b128 v[186:189], v156 offset:20480
	ds_read_b128 v[190:193], v156 offset:21504
	ds_read_b128 v[194:197], v156 offset:22528
	ds_read_b128 v[198:201], v156 offset:23552
	global_load_lds_dwordx4 v[182:183], off
	v_lshl_add_u64 v[218:219], s[26:27], 0, v[130:131]
	s_mov_b32 m0, s38
	s_nop 0
	global_load_lds_dwordx4 v[218:219], off
	s_barrier
	s_waitcnt lgkmcnt(0)
	s_setprio 1
	s_waitcnt lgkmcnt(0)
	v_mfma_f32_16x16x32_bf16 v[60:63], v[138:141], v[166:169], v[60:63]
	v_mfma_f32_16x16x32_bf16 v[56:59], v[146:149], v[166:169], v[56:59]
	v_mfma_f32_16x16x32_bf16 v[52:55], v[138:141], v[174:177], v[52:55]
	v_mfma_f32_16x16x32_bf16 v[48:51], v[146:149], v[174:177], v[48:51]
	v_mfma_f32_16x16x32_bf16 v[40:43], v[138:141], v[186:189], v[40:43]
	v_mfma_f32_16x16x32_bf16 v[32:35], v[146:149], v[186:189], v[32:35]
	v_mfma_f32_16x16x32_bf16 v[24:27], v[138:141], v[194:197], v[24:27]
	v_mfma_f32_16x16x32_bf16 v[16:19], v[146:149], v[194:197], v[16:19]
	v_mfma_f32_16x16x32_bf16 v[60:63], v[142:145], v[170:173], v[60:63]
	v_mfma_f32_16x16x32_bf16 v[56:59], v[162:165], v[170:173], v[56:59]
	v_mfma_f32_16x16x32_bf16 v[52:55], v[142:145], v[178:181], v[52:55]
	v_mfma_f32_16x16x32_bf16 v[48:51], v[162:165], v[178:181], v[48:51]
	v_mfma_f32_16x16x32_bf16 v[40:43], v[142:145], v[190:193], v[40:43]
	v_mfma_f32_16x16x32_bf16 v[32:35], v[162:165], v[190:193], v[32:35]
	v_mfma_f32_16x16x32_bf16 v[24:27], v[142:145], v[198:201], v[24:27]
	v_mfma_f32_16x16x32_bf16 v[16:19], v[162:165], v[198:201], v[16:19]
	s_setprio 0
	s_barrier
; #define PG8_STAGE(bufoff, gbase, voff) do { _Pragma("unroll") for (int _i = 0; _i < 2; ++_i) \
;         __builtin_amdgcn_global_load_lds((const unsigned*)((const char*)(gbase) + (voff)[_i]), (LAS unsigned*)(lds + (bufoff) + ldsw + _i * 8192), 16, 0, 0); } while (0)
; #define PG8_LDA(dst, b, h) do { _Pragma("unroll") for (int m = 0; m < 4; ++m) _Pragma("unroll") for (int k = 0; k < 2; ++k) dst[m][k] = *(const LAS bf16x8*)(lds + PG8_SA(b, h) + aoff + m * 2048 + k * 1024); } while (0)
; #define PG8_LDB(dst, b, h) do { _Pragma("unroll") for (int n = 0; n < 2; ++n) _Pragma("unroll") for (int k = 0; k < 2; ++k) dst[n][k] = *(const LAS bf16x8*)(lds + PG8_SB(b, h) + boff + n * 2048 + k * 1024); } while (0)
; #define PG8_MMA(ai, bj, At, Bt) do { __builtin_amdgcn_s_setprio(1); _Pragma("unroll") for (int m = 0; m < 4; ++m) _Pragma("unroll") for (int n = 0; n < 2; ++n) _Pragma("unroll") for (int k = 0; k < 2; ++k) \
;         acc[ai][bj][m][n] = __builtin_amdgcn_mfma_f32_16x16x32_bf16(Bt[n][k], At[m][k], acc[ai][bj][m][n], 0, 0, 0); __builtin_amdgcn_s_setprio(0); } while (0)
; #define PG8_WAIT_V(n) asm volatile("s_waitcnt vmcnt(" #n ")" ::: "memory")
; #define PG8_WAIT_L(n) asm volatile("s_waitcnt lgkmcnt(" #n ")" ::: "memory")
; #define PG8_BAR __builtin_amdgcn_s_barrier()
; #define PG8_SCHED __builtin_amdgcn_sched_barrier(0)
; template <class Epi, class Sched>
; __device__ __forceinline__ void gemm_phase(LAS unsigned char* lds, const Gemm g, const Sched& S, const Epi& E) {
;     ...
;             PG8_WAIT_V(6); PG8_BAR; PG8_MMA(1, 1, At, B1); PG8_BAR;
;             PG8_LDB(B0, 1, 0); PG8_SCHED; PG8_LDA(At, 1, 0); PG8_STAGE(PG8_SA(0, 1), a2 + hstepA, voffA);
;             PG8_WAIT_L(8); PG8_BAR; PG8_WAIT_L(0); PG8_MMA(0, 0, At, B0); PG8_BAR; PG8_SCHED;
;             PG8_LDB(B1, 1, 1); PG8_STAGE(PG8_SB(1, 0), b3, voffB);
;             PG8_BAR; PG8_WAIT_L(0); if constexpr (!Epi::DIAG) PG8_MMA(0, 1, At, B1); PG8_BAR;
;             PG8_LDA(At, 1, 1); PG8_STAGE(PG8_SA(1, 0), a3, voffA);
;             PG8_BAR; PG8_WAIT_L(0); if constexpr (!Epi::DIAG) PG8_MMA(1, 0, At, B0); PG8_BAR; PG8_SCHED;
	s_add_u32 s70, s24, 0x160000
	s_addc_u32 s71, s25, 0
	s_add_i32 s69, s49, s36
	v_lshl_add_u64 v[138:139], s[70:71], 0, v[128:129]
	s_mov_b32 m0, s69
	s_nop 0
	global_load_lds_dwordx4 v[138:139], off
	v_lshl_add_u64 v[138:139], s[70:71], 0, v[130:131]
	s_add_i32 m0, s69, 0x2000
	s_nop 0
	global_load_lds_dwordx4 v[138:139], off
	s_waitcnt vmcnt(6)
	s_barrier
	s_setprio 1
	v_mfma_f32_16x16x32_bf16 v[44:47], v[202:205], v[166:169], v[44:47]
	v_mfma_f32_16x16x32_bf16 v[36:39], v[210:213], v[166:169], v[36:39]
	v_mfma_f32_16x16x32_bf16 v[28:31], v[202:205], v[174:177], v[28:31]
	v_mfma_f32_16x16x32_bf16 v[20:23], v[210:213], v[174:177], v[20:23]
	v_mfma_f32_16x16x32_bf16 v[12:15], v[202:205], v[186:189], v[12:15]
	v_mfma_f32_16x16x32_bf16 v[8:11], v[210:213], v[186:189], v[8:11]
	v_mfma_f32_16x16x32_bf16 v[4:7], v[202:205], v[194:197], v[4:7]
	v_mfma_f32_16x16x32_bf16 v[0:3], v[210:213], v[194:197], v[0:3]
	v_mfma_f32_16x16x32_bf16 v[44:47], v[206:209], v[170:173], v[44:47]
	v_mfma_f32_16x16x32_bf16 v[36:39], v[214:217], v[170:173], v[36:39]
	v_mfma_f32_16x16x32_bf16 v[28:31], v[206:209], v[178:181], v[28:31]
	v_mfma_f32_16x16x32_bf16 v[20:23], v[214:217], v[178:181], v[20:23]
	v_mfma_f32_16x16x32_bf16 v[12:15], v[206:209], v[190:193], v[12:15]
	v_mfma_f32_16x16x32_bf16 v[8:11], v[214:217], v[190:193], v[8:11]
	v_mfma_f32_16x16x32_bf16 v[4:7], v[206:209], v[198:201], v[4:7]
	v_mfma_f32_16x16x32_bf16 v[0:3], v[214:217], v[198:201], v[0:3]
	s_setprio 0
	s_add_i32 s69, 0, 0x18000
	v_add_u32_e32 v132, s69, v153
	s_barrier
	ds_read_b128 v[138:141], v132
	ds_read_b128 v[142:145], v132 offset:1024
	ds_read_b128 v[146:149], v132 offset:2048
	ds_read_b128 v[162:165], v132 offset:3072
	s_add_u32 s26, s26, 0x160000
	s_addc_u32 s27, s27, 0
	s_mov_b32 m0, s39
	v_lshl_add_u64 v[202:203], s[26:27], 0, v[128:129]
	ds_read_b128 v[166:169], v156 offset:32768
	ds_read_b128 v[170:173], v156 offset:33792
	ds_read_b128 v[174:177], v156 offset:34816
	ds_read_b128 v[178:181], v156 offset:35840
	ds_read_b128 v[186:189], v156 offset:36864
	ds_read_b128 v[190:193], v156 offset:37888
	ds_read_b128 v[194:197], v156 offset:38912
	ds_read_b128 v[198:201], v156 offset:39936
	global_load_lds_dwordx4 v[202:203], off
	v_lshl_add_u64 v[202:203], s[26:27], 0, v[130:131]
	s_mov_b32 m0, s40
	s_nop 0
	global_load_lds_dwordx4 v[202:203], off
	s_waitcnt lgkmcnt(8)
	s_barrier
	s_waitcnt lgkmcnt(0)
	s_setprio 1
	s_waitcnt lgkmcnt(0)
	v_mfma_f32_16x16x32_bf16 v[124:127], v[138:141], v[166:169], v[124:127]
	v_mfma_f32_16x16x32_bf16 v[120:123], v[146:149], v[166:169], v[120:123]
	v_mfma_f32_16x16x32_bf16 v[116:119], v[138:141], v[174:177], v[116:119]
	v_mfma_f32_16x16x32_bf16 v[112:115], v[146:149], v[174:177], v[112:115]
	v_mfma_f32_16x16x32_bf16 v[104:107], v[138:141], v[186:189], v[104:107]
	v_mfma_f32_16x16x32_bf16 v[96:99], v[146:149], v[186:189], v[96:99]
	v_mfma_f32_16x16x32_bf16 v[88:91], v[138:141], v[194:197], v[88:91]
	v_mfma_f32_16x16x32_bf16 v[80:83], v[146:149], v[194:197], v[80:83]
	v_mfma_f32_16x16x32_bf16 v[124:127], v[142:145], v[170:173], v[124:127]
	v_mfma_f32_16x16x32_bf16 v[120:123], v[162:165], v[170:173], v[120:123]
	v_mfma_f32_16x16x32_bf16 v[116:119], v[142:145], v[178:181], v[116:119]
	v_mfma_f32_16x16x32_bf16 v[112:115], v[162:165], v[178:181], v[112:115]
	v_mfma_f32_16x16x32_bf16 v[104:107], v[142:145], v[190:193], v[104:107]
	v_mfma_f32_16x16x32_bf16 v[96:99], v[162:165], v[190:193], v[96:99]
	v_mfma_f32_16x16x32_bf16 v[88:91], v[142:145], v[198:201], v[88:91]
	v_mfma_f32_16x16x32_bf16 v[80:83], v[162:165], v[198:201], v[80:83]
	s_setprio 0
	s_barrier
	s_add_i32 s26, 0, 0x1c000
	s_add_i32 s27, s69, s36
	v_add_u32_e32 v132, s26, v153
	v_lshl_add_u64 v[150:151], v[150:151], 0, s[16:17]
	s_mov_b32 m0, s27
	ds_read_b128 v[202:205], v132
	ds_read_b128 v[206:209], v132 offset:1024
	ds_read_b128 v[210:213], v132 offset:2048
	ds_read_b128 v[214:217], v132 offset:3072
	global_load_lds_dwordx4 v[150:151], off
	v_lshl_add_u64 v[150:151], v[158:159], 0, s[16:17]
	s_add_i32 m0, s27, 0x2000
	s_nop 0
	global_load_lds_dwordx4 v[150:151], off
	s_barrier
	s_waitcnt lgkmcnt(0)
	s_setprio 1
	s_waitcnt lgkmcnt(0)
	v_mfma_f32_16x16x32_bf16 v[108:111], v[202:205], v[166:169], v[108:111]
	v_mfma_f32_16x16x32_bf16 v[100:103], v[210:213], v[166:169], v[100:103]
	v_mfma_f32_16x16x32_bf16 v[92:95], v[202:205], v[174:177], v[92:95]
	v_mfma_f32_16x16x32_bf16 v[84:87], v[210:213], v[174:177], v[84:87]
	v_mfma_f32_16x16x32_bf16 v[76:79], v[202:205], v[186:189], v[76:79]
	v_mfma_f32_16x16x32_bf16 v[72:75], v[210:213], v[186:189], v[72:75]
	v_mfma_f32_16x16x32_bf16 v[68:71], v[202:205], v[194:197], v[68:71]
	v_mfma_f32_16x16x32_bf16 v[64:67], v[210:213], v[194:197], v[64:67]
	v_mfma_f32_16x16x32_bf16 v[108:111], v[206:209], v[170:173], v[108:111]
	v_mfma_f32_16x16x32_bf16 v[100:103], v[214:217], v[170:173], v[100:103]
	v_mfma_f32_16x16x32_bf16 v[92:95], v[206:209], v[178:181], v[92:95]
	v_mfma_f32_16x16x32_bf16 v[84:87], v[214:217], v[178:181], v[84:87]
	v_mfma_f32_16x16x32_bf16 v[76:79], v[206:209], v[190:193], v[76:79]
	v_mfma_f32_16x16x32_bf16 v[72:75], v[214:217], v[190:193], v[72:75]
	v_mfma_f32_16x16x32_bf16 v[68:71], v[206:209], v[198:201], v[68:71]
	v_mfma_f32_16x16x32_bf16 v[64:67], v[214:217], v[198:201], v[64:67]
	s_setprio 0
	s_mov_b32 m0, s45
	v_lshl_add_u64 v[150:151], v[182:183], 0, s[16:17]
	s_barrier
	ds_read_b128 v[166:169], v156 offset:49152
	ds_read_b128 v[170:173], v156 offset:50176
	ds_read_b128 v[174:177], v156 offset:51200
	ds_read_b128 v[178:181], v156 offset:52224
	ds_read_b128 v[186:189], v156 offset:53248
	ds_read_b128 v[190:193], v156 offset:54272
	ds_read_b128 v[194:197], v156 offset:55296
	ds_read_b128 v[198:201], v156 offset:56320
	global_load_lds_dwordx4 v[150:151], off
	v_lshl_add_u64 v[150:151], v[218:219], 0, s[16:17]
	s_mov_b32 m0, s46
	s_nop 0
	global_load_lds_dwordx4 v[150:151], off
	s_barrier
; #define PG8_STAGE(bufoff, gbase, voff) do { _Pragma("unroll") for (int _i = 0; _i < 2; ++_i) \
;         __builtin_amdgcn_global_load_lds((const unsigned*)((const char*)(gbase) + (voff)[_i]), (LAS unsigned*)(lds + (bufoff) + ldsw + _i * 8192), 16, 0, 0); } while (0)
; #define PG8_MMA(ai, bj, At, Bt) do { __builtin_amdgcn_s_setprio(1); _Pragma("unroll") for (int m = 0; m < 4; ++m) _Pragma("unroll") for (int n = 0; n < 2; ++n) _Pragma("unroll") for (int k = 0; k < 2; ++k) \
;         acc[ai][bj][m][n] = __builtin_amdgcn_mfma_f32_16x16x32_bf16(Bt[n][k], At[m][k], acc[ai][bj][m][n], 0, 0, 0); __builtin_amdgcn_s_setprio(0); } while (0)
; #define PG8_WAIT_V(n) asm volatile("s_waitcnt vmcnt(" #n ")" ::: "memory")
; #define PG8_WAIT_L(n) asm volatile("s_waitcnt lgkmcnt(" #n ")" ::: "memory")
; #define PG8_BAR __builtin_amdgcn_s_barrier()
; #define PG8_SCHED __builtin_amdgcn_sched_barrier(0)
; template <class Epi, class Sched>
; __device__ __forceinline__ void gemm_phase(LAS unsigned char* lds, const Gemm g, const Sched& S, const Epi& E) {
;     ...
;             PG8_BAR; PG8_WAIT_L(0); if constexpr (!Epi::DIAG) PG8_MMA(1, 0, At, B0); PG8_BAR; PG8_SCHED;
;             PG8_STAGE(PG8_SB(1, 1), b3 + hstepB, voffB);
;             PG8_WAIT_V(6); PG8_BAR; PG8_MMA(1, 1, At, B1); PG8_BAR;
;     __device__ __forceinline__ void operator()(const Acc& acc, const Unit& u, int wr, int wc, int fr, int fq) const {
;     ...
; #pragma unroll
;         for (int ai = 0; ai < 2; ++ai)
; #pragma unroll
;             for (int m = 0; m < 4; ++m) { const int row = row0 + ai * HALF + m * 16; const int b = bidx_of_row(row);
;                 const float* xr = (row < TP) ? x0p + (size_t)row * DM : x0s + (size_t)(row - TP) * DM; const float* gr = gate + (size_t)b * MODW; float* orow = X1 + (size_t)row * DM;
; #pragma unroll
;                 for (int bj = 0; bj < 2; ++bj)
; #pragma unroll
;                     for (int n = 0; n < 2; ++n) { const int c = col0 + bj * HALF + n * 16; const f32x4 xv = *(const f32x4*)(xr + c), gv = *(const f32x4*)(gr + c);
;                         *(f32x4*)(orow + c) = xv + gv * acc[ai][bj][m][n]; } }
	s_waitcnt lgkmcnt(0)
	s_setprio 1
	s_waitcnt lgkmcnt(0)
	v_mfma_f32_16x16x32_bf16 v[60:63], v[138:141], v[166:169], v[60:63]
	v_mfma_f32_16x16x32_bf16 v[56:59], v[146:149], v[166:169], v[56:59]
	v_mfma_f32_16x16x32_bf16 v[52:55], v[138:141], v[174:177], v[52:55]
	v_mfma_f32_16x16x32_bf16 v[48:51], v[146:149], v[174:177], v[48:51]
	v_mfma_f32_16x16x32_bf16 v[40:43], v[138:141], v[186:189], v[40:43]
	v_mfma_f32_16x16x32_bf16 v[32:35], v[146:149], v[186:189], v[32:35]
	v_mfma_f32_16x16x32_bf16 v[24:27], v[138:141], v[194:197], v[24:27]
	v_mfma_f32_16x16x32_bf16 v[16:19], v[146:149], v[194:197], v[16:19]
	v_mfma_f32_16x16x32_bf16 v[60:63], v[142:145], v[170:173], v[60:63]
	v_mfma_f32_16x16x32_bf16 v[56:59], v[162:165], v[170:173], v[56:59]
	v_mfma_f32_16x16x32_bf16 v[52:55], v[142:145], v[178:181], v[52:55]
	v_mfma_f32_16x16x32_bf16 v[48:51], v[162:165], v[178:181], v[48:51]
	v_mfma_f32_16x16x32_bf16 v[40:43], v[142:145], v[190:193], v[40:43]
	v_mfma_f32_16x16x32_bf16 v[32:35], v[162:165], v[190:193], v[32:35]
	v_mfma_f32_16x16x32_bf16 v[24:27], v[142:145], v[198:201], v[24:27]
	v_mfma_f32_16x16x32_bf16 v[16:19], v[162:165], v[198:201], v[16:19]
	s_setprio 0
	s_barrier
	s_add_u32 s24, s24, 0x160080
	s_addc_u32 s25, s25, 0
	s_add_i32 s26, s26, s36
	v_lshl_add_u64 v[138:139], s[24:25], 0, v[128:129]
	s_mov_b32 m0, s26
	s_nop 0
	global_load_lds_dwordx4 v[138:139], off
	v_lshl_add_u64 v[138:139], s[24:25], 0, v[130:131]
	s_add_i32 m0, s26, 0x2000
	s_nop 0
	global_load_lds_dwordx4 v[138:139], off
	s_waitcnt vmcnt(6)
	s_barrier
	s_setprio 1
	v_mfma_f32_16x16x32_bf16 v[44:47], v[202:205], v[166:169], v[44:47]
	v_mfma_f32_16x16x32_bf16 v[36:39], v[210:213], v[166:169], v[36:39]
	v_mfma_f32_16x16x32_bf16 v[28:31], v[202:205], v[174:177], v[28:31]
	v_mfma_f32_16x16x32_bf16 v[20:23], v[210:213], v[174:177], v[20:23]
	v_mfma_f32_16x16x32_bf16 v[12:15], v[202:205], v[186:189], v[12:15]
	v_mfma_f32_16x16x32_bf16 v[8:11], v[210:213], v[186:189], v[8:11]
	v_mfma_f32_16x16x32_bf16 v[4:7], v[202:205], v[194:197], v[4:7]
	v_mfma_f32_16x16x32_bf16 v[0:3], v[210:213], v[194:197], v[0:3]
	v_mfma_f32_16x16x32_bf16 v[44:47], v[206:209], v[170:173], v[44:47]
	v_mfma_f32_16x16x32_bf16 v[36:39], v[214:217], v[170:173], v[36:39]
	v_mfma_f32_16x16x32_bf16 v[28:31], v[206:209], v[178:181], v[28:31]
	v_mfma_f32_16x16x32_bf16 v[20:23], v[214:217], v[178:181], v[20:23]
	v_mfma_f32_16x16x32_bf16 v[12:15], v[206:209], v[190:193], v[12:15]
	v_mfma_f32_16x16x32_bf16 v[8:11], v[214:217], v[190:193], v[8:11]
	v_mfma_f32_16x16x32_bf16 v[4:7], v[206:209], v[198:201], v[4:7]
	v_mfma_f32_16x16x32_bf16 v[0:3], v[214:217], v[198:201], v[0:3]
	s_setprio 0
	s_mov_b32 s73, s74
	s_cmp_ge_u32 s68, s66
	s_mov_b32 s24, s68
	s_barrier
	s_cbranch_scc0 .LBB0_1915
	s_lshl_b32 s24, s65, 8
	s_add_i32 s24, s24, s44
	v_or_b32_e32 v138, s24, v152
	v_lshl_or_b32 v142, s64, 8, v154
	s_cmp_gt_i32 s8, -1
	v_add_u32_e32 v140, 0xffffe000, v138
	s_mov_b64 s[6:7], -1
	s_cbranch_scc1 .LBB0_1950
	v_cmp_gt_i32_e32 vcc, s41, v138
	v_cmp_lt_i32_e64 s[6:7], s50, v138
	s_and_saveexec_b64 s[26:27], s[6:7]
	s_xor_b64 s[6:7], exec, s[26:27]
	v_mov_b32_e32 v141, v133
	v_lshlrev_b64 v[144:145], 13, v[140:141]
	v_mov_b32_e32 v139, v133
	v_lshl_add_u64 v[148:149], s[12:13], 0, v[144:145]
	v_lshlrev_b64 v[146:147], 13, v[138:139]
	s_andn2_saveexec_b64 s[6:7], s[6:7]
	v_ashrrev_i32_e32 v139, 31, v138
	v_lshlrev_b64 v[146:147], 13, v[138:139]
	v_lshl_add_u64 v[148:149], s[10:11], 0, v[146:147]
	s_or_b64 exec, exec, s[6:7]
	s_ashr_i32 s24, s24, 11
	v_lshrrev_b32_e32 v132, 2, v140
	v_or_b32_e32 v132, 4, v132
	v_mov_b32_e32 v139, s24
	v_cndmask_b32_e32 v132, v132, v139, vcc
	v_mov_b64_e32 v[144:145], s[14:15]
	v_ashrrev_i32_e32 v143, 31, v142
	v_mad_i64_i32 v[158:159], s[6:7], v132, s48, v[144:145]
	v_lshlrev_b64 v[144:145], 2, v[142:143]
	v_lshl_add_u64 v[166:167], v[148:149], 0, v[144:145]
	v_lshl_add_u64 v[158:159], v[158:159], 0, v[144:145]
	global_load_dwordx4 v[186:189], v[166:167], off
	global_load_dwordx4 v[202:205], v[158:159], off
	global_load_dwordx4 v[190:193], v[166:167], off offset:64
	global_load_dwordx4 v[206:209], v[158:159], off offset:64
	global_load_dwordx4 v[194:197], v[166:167], off offset:512
	global_load_dwordx4 v[210:213], v[158:159], off offset:512
	global_load_dwordx4 v[198:201], v[166:167], off offset:576
	global_load_dwordx4 v[214:217], v[158:159], off offset:576
	v_lshl_add_u64 v[146:147], s[10:11], 0, v[146:147]
	v_lshl_add_u64 v[168:169], v[146:147], 0, v[144:145]
	v_add_u32_e32 v132, 0xffffe010, v138
	s_waitcnt vmcnt(6)
	v_pk_fma_f32 v[188:189], v[126:127], v[204:205], v[188:189]
	v_pk_fma_f32 v[186:187], v[124:125], v[202:203], v[186:187]
	global_store_dwordx4 v[168:169], v[186:189], off
	v_or_b32_e32 v150, 16, v138
	v_cmp_gt_i32_e32 vcc, s41, v150
	v_cmp_lt_i32_e64 s[6:7], s50, v150
	s_waitcnt vmcnt(5)
	v_pk_fma_f32 v[192:193], v[122:123], v[208:209], v[192:193]
	v_pk_fma_f32 v[190:191], v[120:121], v[206:207], v[190:191]
	global_store_dwordx4 v[168:169], v[190:193], off offset:64
	s_waitcnt vmcnt(4)
	v_pk_fma_f32 v[196:197], v[110:111], v[212:213], v[196:197]
	v_pk_fma_f32 v[194:195], v[108:109], v[210:211], v[194:195]
	global_store_dwordx4 v[168:169], v[194:197], off offset:512
	s_waitcnt vmcnt(3)
;     __device__ __forceinline__ void operator()(const Acc& acc, const Unit& u, int wr, int wc, int fr, int fq) const {
;     ...
; #pragma unroll
;         for (int ai = 0; ai < 2; ++ai)
; #pragma unroll
;             for (int m = 0; m < 4; ++m) { const int row = row0 + ai * HALF + m * 16; const int b = bidx_of_row(row);
;                 const float* xr = (row < TP) ? x0p + (size_t)row * DM : x0s + (size_t)(row - TP) * DM; const float* gr = gate + (size_t)b * MODW; float* orow = X1 + (size_t)row * DM;
; #pragma unroll
;                 for (int bj = 0; bj < 2; ++bj)
; #pragma unroll
;                     for (int n = 0; n < 2; ++n) { const int c = col0 + bj * HALF + n * 16; const f32x4 xv = *(const f32x4*)(xr + c), gv = *(const f32x4*)(gr + c);
;                         *(f32x4*)(orow + c) = xv + gv * acc[ai][bj][m][n]; } }
	v_pk_fma_f32 v[200:201], v[102:103], v[216:217], v[200:201]
	v_pk_fma_f32 v[198:199], v[100:101], v[214:215], v[198:199]
	global_store_dwordx4 v[168:169], v[198:201], off offset:576
	s_and_saveexec_b64 s[26:27], s[6:7]
	s_xor_b64 s[6:7], exec, s[26:27]
	v_lshlrev_b64 v[146:147], 13, v[132:133]
	v_mov_b32_e32 v151, v133
	v_lshl_add_u64 v[148:149], s[12:13], 0, v[146:147]
	v_lshlrev_b64 v[146:147], 13, v[150:151]
	s_andn2_saveexec_b64 s[6:7], s[6:7]
	v_ashrrev_i32_e32 v151, 31, v150
	v_lshlrev_b64 v[146:147], 13, v[150:151]
	v_lshl_add_u64 v[148:149], s[10:11], 0, v[146:147]
	s_or_b64 exec, exec, s[6:7]
	v_lshrrev_b32_e32 v132, 2, v132
	v_add_u32_e32 v132, 4, v132
	v_mov_b32_e32 v139, s24
	v_cndmask_b32_e32 v132, v132, v139, vcc
	v_mov_b64_e32 v[150:151], s[14:15]
	v_mad_i64_i32 v[158:159], s[6:7], v132, s48, v[150:151]
	v_lshl_add_u64 v[166:167], v[148:149], 0, v[144:145]
	v_lshl_add_u64 v[158:159], v[158:159], 0, v[144:145]
	global_load_dwordx4 v[186:189], v[166:167], off
	global_load_dwordx4 v[202:205], v[158:159], off
	global_load_dwordx4 v[190:193], v[166:167], off offset:64
	global_load_dwordx4 v[206:209], v[158:159], off offset:64
	global_load_dwordx4 v[194:197], v[166:167], off offset:512
	global_load_dwordx4 v[210:213], v[158:159], off offset:512
	global_load_dwordx4 v[198:201], v[166:167], off offset:576
	global_load_dwordx4 v[214:217], v[158:159], off offset:576
	v_lshl_add_u64 v[146:147], s[10:11], 0, v[146:147]
	v_lshl_add_u64 v[168:169], v[146:147], 0, v[144:145]
	v_add_u32_e32 v132, 0xffffe020, v138
	s_waitcnt vmcnt(6)
	v_pk_fma_f32 v[188:189], v[118:119], v[204:205], v[188:189]
	v_pk_fma_f32 v[186:187], v[116:117], v[202:203], v[186:187]
	global_store_dwordx4 v[168:169], v[186:189], off
	v_or_b32_e32 v150, 32, v138
	v_cmp_gt_i32_e32 vcc, s41, v150
	v_cmp_lt_i32_e64 s[6:7], s50, v150
	s_waitcnt vmcnt(5)
	v_pk_fma_f32 v[192:193], v[114:115], v[208:209], v[192:193]
	v_pk_fma_f32 v[190:191], v[112:113], v[206:207], v[190:191]
	global_store_dwordx4 v[168:169], v[190:193], off offset:64
	s_waitcnt vmcnt(4)
	v_pk_fma_f32 v[196:197], v[94:95], v[212:213], v[196:197]
	v_pk_fma_f32 v[194:195], v[92:93], v[210:211], v[194:195]
	global_store_dwordx4 v[168:169], v[194:197], off offset:512
	s_waitcnt vmcnt(3)
	v_pk_fma_f32 v[200:201], v[86:87], v[216:217], v[200:201]
	v_pk_fma_f32 v[198:199], v[84:85], v[214:215], v[198:199]
	global_store_dwordx4 v[168:169], v[198:201], off offset:576
	s_and_saveexec_b64 s[26:27], s[6:7]
	s_xor_b64 s[6:7], exec, s[26:27]
	v_lshlrev_b64 v[146:147], 13, v[132:133]
	v_mov_b32_e32 v151, v133
	v_lshl_add_u64 v[148:149], s[12:13], 0, v[146:147]
	v_lshlrev_b64 v[146:147], 13, v[150:151]
	s_andn2_saveexec_b64 s[6:7], s[6:7]
	v_ashrrev_i32_e32 v151, 31, v150
	v_lshlrev_b64 v[146:147], 13, v[150:151]
	v_lshl_add_u64 v[148:149], s[10:11], 0, v[146:147]
	s_or_b64 exec, exec, s[6:7]
	v_lshrrev_b32_e32 v132, 2, v132
	v_or_b32_e32 v132, 4, v132
	v_mov_b32_e32 v139, s24
	v_cndmask_b32_e32 v132, v132, v139, vcc
	v_mov_b64_e32 v[150:151], s[14:15]
	v_mad_i64_i32 v[158:159], s[6:7], v132, s48, v[150:151]
	v_lshl_add_u64 v[166:167], v[148:149], 0, v[144:145]
	v_lshl_add_u64 v[158:159], v[158:159], 0, v[144:145]
	global_load_dwordx4 v[186:189], v[166:167], off
	global_load_dwordx4 v[202:205], v[158:159], off
	global_load_dwordx4 v[190:193], v[166:167], off offset:64
	global_load_dwordx4 v[206:209], v[158:159], off offset:64
	global_load_dwordx4 v[194:197], v[166:167], off offset:512
	global_load_dwordx4 v[210:213], v[158:159], off offset:512
	global_load_dwordx4 v[198:201], v[166:167], off offset:576
	global_load_dwordx4 v[214:217], v[158:159], off offset:576
	v_lshl_add_u64 v[146:147], s[10:11], 0, v[146:147]
	v_lshl_add_u64 v[168:169], v[146:147], 0, v[144:145]
	v_add_u32_e32 v132, 0xffffe030, v138
	s_waitcnt vmcnt(6)
	v_pk_fma_f32 v[188:189], v[106:107], v[204:205], v[188:189]
	v_pk_fma_f32 v[186:187], v[104:105], v[202:203], v[186:187]
	global_store_dwordx4 v[168:169], v[186:189], off
	v_or_b32_e32 v150, 48, v138
	v_cmp_gt_i32_e32 vcc, s41, v150
	v_cmp_lt_i32_e64 s[6:7], s50, v150
	s_waitcnt vmcnt(5)
	v_pk_fma_f32 v[192:193], v[98:99], v[208:209], v[192:193]
	v_pk_fma_f32 v[190:191], v[96:97], v[206:207], v[190:191]
	global_store_dwordx4 v[168:169], v[190:193], off offset:64
	s_waitcnt vmcnt(4)
	v_pk_fma_f32 v[196:197], v[78:79], v[212:213], v[196:197]
	v_pk_fma_f32 v[194:195], v[76:77], v[210:211], v[194:195]
	global_store_dwordx4 v[168:169], v[194:197], off offset:512
	s_waitcnt vmcnt(3)
	v_pk_fma_f32 v[200:201], v[74:75], v[216:217], v[200:201]
	v_pk_fma_f32 v[198:199], v[72:73], v[214:215], v[198:199]
	global_store_dwordx4 v[168:169], v[198:201], off offset:576
	s_and_saveexec_b64 s[26:27], s[6:7]
	s_xor_b64 s[6:7], exec, s[26:27]
	v_lshlrev_b64 v[146:147], 13, v[132:133]
	v_mov_b32_e32 v151, v133
	v_lshl_add_u64 v[148:149], s[12:13], 0, v[146:147]
	v_lshlrev_b64 v[146:147], 13, v[150:151]
	s_andn2_saveexec_b64 s[6:7], s[6:7]
	v_ashrrev_i32_e32 v151, 31, v150
	v_lshlrev_b64 v[146:147], 13, v[150:151]
	v_lshl_add_u64 v[148:149], s[10:11], 0, v[146:147]
	s_or_b64 exec, exec, s[6:7]
	v_lshrrev_b32_e32 v132, 2, v132
	v_add_u32_e32 v132, 4, v132
	v_mov_b32_e32 v139, s24
	v_cndmask_b32_e32 v132, v132, v139, vcc
	v_mov_b64_e32 v[150:151], s[14:15]
	v_mad_i64_i32 v[158:159], s[6:7], v132, s48, v[150:151]
	v_lshl_add_u64 v[166:167], v[148:149], 0, v[144:145]
	v_lshl_add_u64 v[158:159], v[158:159], 0, v[144:145]
	global_load_dwordx4 v[186:189], v[166:167], off
	global_load_dwordx4 v[202:205], v[158:159], off
	global_load_dwordx4 v[190:193], v[166:167], off offset:64
	global_load_dwordx4 v[206:209], v[158:159], off offset:64
	global_load_dwordx4 v[194:197], v[166:167], off offset:512
	global_load_dwordx4 v[210:213], v[158:159], off offset:512
	global_load_dwordx4 v[198:201], v[166:167], off offset:576
	global_load_dwordx4 v[214:217], v[158:159], off offset:576
	v_lshl_add_u64 v[146:147], s[10:11], 0, v[146:147]
	v_lshl_add_u64 v[168:169], v[146:147], 0, v[144:145]
	v_cmp_gt_i32_e32 vcc, s51, v138
	v_cmp_lt_i32_e64 s[6:7], s52, v138
	v_add_u32_e32 v132, 0xffffe080, v138
	s_waitcnt vmcnt(6)
;     __device__ __forceinline__ void operator()(const Acc& acc, const Unit& u, int wr, int wc, int fr, int fq) const {
;     ...
; #pragma unroll
;         for (int ai = 0; ai < 2; ++ai)
; #pragma unroll
;             for (int m = 0; m < 4; ++m) { const int row = row0 + ai * HALF + m * 16; const int b = bidx_of_row(row);
;                 const float* xr = (row < TP) ? x0p + (size_t)row * DM : x0s + (size_t)(row - TP) * DM; const float* gr = gate + (size_t)b * MODW; float* orow = X1 + (size_t)row * DM;
; #pragma unroll
;                 for (int bj = 0; bj < 2; ++bj)
; #pragma unroll
;                     for (int n = 0; n < 2; ++n) { const int c = col0 + bj * HALF + n * 16; const f32x4 xv = *(const f32x4*)(xr + c), gv = *(const f32x4*)(gr + c);
;                         *(f32x4*)(orow + c) = xv + gv * acc[ai][bj][m][n]; } }
	v_pk_fma_f32 v[188:189], v[90:91], v[204:205], v[188:189]
	v_pk_fma_f32 v[186:187], v[88:89], v[202:203], v[186:187]
	global_store_dwordx4 v[168:169], v[186:189], off
	s_waitcnt vmcnt(5)
	v_pk_fma_f32 v[192:193], v[82:83], v[208:209], v[192:193]
	v_pk_fma_f32 v[190:191], v[80:81], v[206:207], v[190:191]
	global_store_dwordx4 v[168:169], v[190:193], off offset:64
	s_waitcnt vmcnt(4)
	v_pk_fma_f32 v[196:197], v[70:71], v[212:213], v[196:197]
	v_pk_fma_f32 v[194:195], v[68:69], v[210:211], v[194:195]
	global_store_dwordx4 v[168:169], v[194:197], off offset:512
	v_add_u32_e32 v146, 0x80, v138
	s_waitcnt vmcnt(3)
	v_pk_fma_f32 v[200:201], v[66:67], v[216:217], v[200:201]
	v_pk_fma_f32 v[198:199], v[64:65], v[214:215], v[198:199]
	global_store_dwordx4 v[168:169], v[198:201], off offset:576
	s_and_saveexec_b64 s[24:25], s[6:7]
	s_xor_b64 s[6:7], exec, s[24:25]
	v_lshlrev_b64 v[148:149], 13, v[132:133]
	v_mov_b32_e32 v147, v133
	v_lshl_add_u64 v[150:151], s[12:13], 0, v[148:149]
	v_lshlrev_b64 v[148:149], 13, v[146:147]
	s_andn2_saveexec_b64 s[6:7], s[6:7]
	v_ashrrev_i32_e32 v147, 31, v146
	v_lshlrev_b64 v[148:149], 13, v[146:147]
	v_lshl_add_u64 v[150:151], s[10:11], 0, v[148:149]
	s_or_b64 exec, exec, s[6:7]
	v_lshrrev_b32_e32 v132, 2, v132
	v_ashrrev_i32_e32 v139, 11, v146
	v_or_b32_e32 v132, 4, v132
	v_cndmask_b32_e32 v132, v132, v139, vcc
	v_mov_b64_e32 v[146:147], s[14:15]
	v_mad_i64_i32 v[146:147], s[6:7], v132, s48, v[146:147]
	v_lshl_add_u64 v[150:151], v[150:151], 0, v[144:145]
	v_lshl_add_u64 v[158:159], v[146:147], 0, v[144:145]
	global_load_dwordx4 v[186:189], v[150:151], off
	global_load_dwordx4 v[202:205], v[158:159], off
	global_load_dwordx4 v[190:193], v[150:151], off offset:64
	global_load_dwordx4 v[206:209], v[158:159], off offset:64
	global_load_dwordx4 v[194:197], v[150:151], off offset:512
	global_load_dwordx4 v[210:213], v[158:159], off offset:512
	global_load_dwordx4 v[198:201], v[150:151], off offset:576
	global_load_dwordx4 v[214:217], v[158:159], off offset:576
	v_lshl_add_u64 v[146:147], s[10:11], 0, v[148:149]
	v_lshl_add_u64 v[170:171], v[146:147], 0, v[144:145]
	v_cmp_gt_i32_e32 vcc, s53, v138
	v_cmp_lt_i32_e64 s[6:7], s54, v138
	v_add_u32_e32 v132, 0xffffe090, v138
	s_waitcnt vmcnt(6)
	v_pk_fma_f32 v[148:149], v[62:63], v[204:205], v[188:189]
	v_pk_fma_f32 v[146:147], v[60:61], v[202:203], v[186:187]
	global_store_dwordx4 v[170:171], v[146:149], off
	s_waitcnt vmcnt(5)
	v_pk_fma_f32 v[192:193], v[58:59], v[208:209], v[192:193]
	v_pk_fma_f32 v[190:191], v[56:57], v[206:207], v[190:191]
	global_store_dwordx4 v[170:171], v[190:193], off offset:64
	s_waitcnt vmcnt(4)
	v_pk_fma_f32 v[196:197], v[46:47], v[212:213], v[196:197]
	v_pk_fma_f32 v[194:195], v[44:45], v[210:211], v[194:195]
	global_store_dwordx4 v[170:171], v[194:197], off offset:512
	v_add_u32_e32 v150, 0x90, v138
	s_waitcnt vmcnt(3)
	v_pk_fma_f32 v[200:201], v[38:39], v[216:217], v[200:201]
	v_pk_fma_f32 v[198:199], v[36:37], v[214:215], v[198:199]
	global_store_dwordx4 v[170:171], v[198:201], off offset:576
	s_and_saveexec_b64 s[24:25], s[6:7]
	s_xor_b64 s[6:7], exec, s[24:25]
	v_lshlrev_b64 v[146:147], 13, v[132:133]
	v_mov_b32_e32 v151, v133
	v_lshl_add_u64 v[148:149], s[12:13], 0, v[146:147]
	v_lshlrev_b64 v[146:147], 13, v[150:151]
	s_andn2_saveexec_b64 s[6:7], s[6:7]
	v_ashrrev_i32_e32 v151, 31, v150
	v_lshlrev_b64 v[146:147], 13, v[150:151]
	v_lshl_add_u64 v[148:149], s[10:11], 0, v[146:147]
	s_or_b64 exec, exec, s[6:7]
	v_lshrrev_b32_e32 v132, 2, v132
	v_add_u32_e32 v132, 4, v132
	v_cndmask_b32_e32 v132, v132, v139, vcc
	v_mov_b64_e32 v[150:151], s[14:15]
	v_mad_i64_i32 v[158:159], s[6:7], v132, s48, v[150:151]
	v_lshl_add_u64 v[166:167], v[148:149], 0, v[144:145]
	v_lshl_add_u64 v[158:159], v[158:159], 0, v[144:145]
	global_load_dwordx4 v[186:189], v[166:167], off
	global_load_dwordx4 v[202:205], v[158:159], off
	global_load_dwordx4 v[190:193], v[166:167], off offset:64
	global_load_dwordx4 v[206:209], v[158:159], off offset:64
	global_load_dwordx4 v[194:197], v[166:167], off offset:512
	global_load_dwordx4 v[210:213], v[158:159], off offset:512
	global_load_dwordx4 v[198:201], v[166:167], off offset:576
	global_load_dwordx4 v[214:217], v[158:159], off offset:576
	v_lshl_add_u64 v[146:147], s[10:11], 0, v[146:147]
	v_lshl_add_u64 v[168:169], v[146:147], 0, v[144:145]
	v_cmp_gt_i32_e32 vcc, s55, v138
	v_cmp_lt_i32_e64 s[6:7], s56, v138
	v_add_u32_e32 v132, 0xffffe0a0, v138
	s_waitcnt vmcnt(6)
	v_pk_fma_f32 v[188:189], v[54:55], v[204:205], v[188:189]
	v_pk_fma_f32 v[186:187], v[52:53], v[202:203], v[186:187]
	global_store_dwordx4 v[168:169], v[186:189], off
	v_add_u32_e32 v150, 0xa0, v138
	s_waitcnt vmcnt(5)
;     __device__ __forceinline__ void operator()(const Acc& acc, const Unit& u, int wr, int wc, int fr, int fq) const {
;     ...
; #pragma unroll
;         for (int ai = 0; ai < 2; ++ai)
; #pragma unroll
;             for (int m = 0; m < 4; ++m) { const int row = row0 + ai * HALF + m * 16; const int b = bidx_of_row(row);
;                 const float* xr = (row < TP) ? x0p + (size_t)row * DM : x0s + (size_t)(row - TP) * DM; const float* gr = gate + (size_t)b * MODW; float* orow = X1 + (size_t)row * DM;
; #pragma unroll
;                 for (int bj = 0; bj < 2; ++bj)
; #pragma unroll
;                     for (int n = 0; n < 2; ++n) { const int c = col0 + bj * HALF + n * 16; const f32x4 xv = *(const f32x4*)(xr + c), gv = *(const f32x4*)(gr + c);
;                         *(f32x4*)(orow + c) = xv + gv * acc[ai][bj][m][n]; } }
	v_pk_fma_f32 v[192:193], v[50:51], v[208:209], v[192:193]
	v_pk_fma_f32 v[190:191], v[48:49], v[206:207], v[190:191]
	global_store_dwordx4 v[168:169], v[190:193], off offset:64
	s_waitcnt vmcnt(4)
	v_pk_fma_f32 v[196:197], v[30:31], v[212:213], v[196:197]
	v_pk_fma_f32 v[194:195], v[28:29], v[210:211], v[194:195]
	global_store_dwordx4 v[168:169], v[194:197], off offset:512
	s_waitcnt vmcnt(3)
	v_pk_fma_f32 v[200:201], v[22:23], v[216:217], v[200:201]
	v_pk_fma_f32 v[198:199], v[20:21], v[214:215], v[198:199]
	global_store_dwordx4 v[168:169], v[198:201], off offset:576
	s_and_saveexec_b64 s[24:25], s[6:7]
	s_xor_b64 s[6:7], exec, s[24:25]
	v_lshlrev_b64 v[146:147], 13, v[132:133]
	v_mov_b32_e32 v151, v133
	v_lshl_add_u64 v[148:149], s[12:13], 0, v[146:147]
	v_lshlrev_b64 v[146:147], 13, v[150:151]
	s_andn2_saveexec_b64 s[6:7], s[6:7]
	v_ashrrev_i32_e32 v151, 31, v150
	v_lshlrev_b64 v[146:147], 13, v[150:151]
	v_lshl_add_u64 v[148:149], s[10:11], 0, v[146:147]
	s_or_b64 exec, exec, s[6:7]
	v_lshrrev_b32_e32 v132, 2, v132
	v_or_b32_e32 v132, 4, v132
	v_cndmask_b32_e32 v132, v132, v139, vcc
	v_mov_b64_e32 v[150:151], s[14:15]
	v_mad_i64_i32 v[158:159], s[6:7], v132, s48, v[150:151]
	v_lshl_add_u64 v[166:167], v[148:149], 0, v[144:145]
	v_lshl_add_u64 v[158:159], v[158:159], 0, v[144:145]
	global_load_dwordx4 v[186:189], v[166:167], off
	global_load_dwordx4 v[202:205], v[158:159], off
	global_load_dwordx4 v[190:193], v[166:167], off offset:64
	global_load_dwordx4 v[206:209], v[158:159], off offset:64
	global_load_dwordx4 v[194:197], v[166:167], off offset:512
	global_load_dwordx4 v[210:213], v[158:159], off offset:512
	global_load_dwordx4 v[198:201], v[166:167], off offset:576
	global_load_dwordx4 v[214:217], v[158:159], off offset:576
	v_lshl_add_u64 v[146:147], s[10:11], 0, v[146:147]
	v_lshl_add_u64 v[168:169], v[146:147], 0, v[144:145]
	v_cmp_gt_i32_e32 vcc, s57, v138
	v_cmp_lt_i32_e64 s[6:7], s58, v138
	v_add_u32_e32 v132, 0xffffe0b0, v138
	s_waitcnt vmcnt(6)
	v_pk_fma_f32 v[188:189], v[42:43], v[204:205], v[188:189]
	v_pk_fma_f32 v[186:187], v[40:41], v[202:203], v[186:187]
	global_store_dwordx4 v[168:169], v[186:189], off
	v_add_u32_e32 v150, 0xb0, v138
	s_waitcnt vmcnt(5)
	v_pk_fma_f32 v[192:193], v[34:35], v[208:209], v[192:193]
	v_pk_fma_f32 v[190:191], v[32:33], v[206:207], v[190:191]
	global_store_dwordx4 v[168:169], v[190:193], off offset:64
	s_waitcnt vmcnt(4)
	v_pk_fma_f32 v[196:197], v[14:15], v[212:213], v[196:197]
	v_pk_fma_f32 v[194:195], v[12:13], v[210:211], v[194:195]
	global_store_dwordx4 v[168:169], v[194:197], off offset:512
	s_waitcnt vmcnt(3)
	v_pk_fma_f32 v[200:201], v[10:11], v[216:217], v[200:201]
	v_pk_fma_f32 v[198:199], v[8:9], v[214:215], v[198:199]
	global_store_dwordx4 v[168:169], v[198:201], off offset:576
	s_and_saveexec_b64 s[24:25], s[6:7]
	s_xor_b64 s[6:7], exec, s[24:25]
	v_lshlrev_b64 v[146:147], 13, v[132:133]
	v_mov_b32_e32 v151, v133
	v_lshl_add_u64 v[148:149], s[12:13], 0, v[146:147]
	v_lshlrev_b64 v[146:147], 13, v[150:151]
	s_andn2_saveexec_b64 s[6:7], s[6:7]
	v_ashrrev_i32_e32 v151, 31, v150
	v_lshlrev_b64 v[146:147], 13, v[150:151]
	v_lshl_add_u64 v[148:149], s[10:11], 0, v[146:147]
	s_or_b64 exec, exec, s[6:7]
	v_lshrrev_b32_e32 v132, 2, v132
	v_add_u32_e32 v132, 4, v132
	v_cndmask_b32_e32 v132, v132, v139, vcc
	v_mov_b64_e32 v[150:151], s[14:15]
	v_mad_i64_i32 v[158:159], s[6:7], v132, s48, v[150:151]
	v_lshl_add_u64 v[166:167], v[148:149], 0, v[144:145]
	v_lshl_add_u64 v[158:159], v[158:159], 0, v[144:145]
	global_load_dwordx4 v[186:189], v[166:167], off
	global_load_dwordx4 v[202:205], v[158:159], off
	global_load_dwordx4 v[190:193], v[166:167], off offset:64
	global_load_dwordx4 v[206:209], v[158:159], off offset:64
	global_load_dwordx4 v[194:197], v[166:167], off offset:512
	global_load_dwordx4 v[210:213], v[158:159], off offset:512
	global_load_dwordx4 v[198:201], v[166:167], off offset:576
	global_load_dwordx4 v[214:217], v[158:159], off offset:576
	v_lshl_add_u64 v[146:147], s[10:11], 0, v[146:147]
	v_lshl_add_u64 v[168:169], v[146:147], 0, v[144:145]
	s_mov_b64 s[6:7], 0
	s_waitcnt vmcnt(6)
	v_pk_fma_f32 v[146:147], v[26:27], v[204:205], v[188:189]
	v_pk_fma_f32 v[144:145], v[24:25], v[202:203], v[186:187]
	global_store_dwordx4 v[168:169], v[144:147], off
	s_waitcnt vmcnt(5)
	v_pk_fma_f32 v[192:193], v[18:19], v[208:209], v[192:193]
	v_pk_fma_f32 v[190:191], v[16:17], v[206:207], v[190:191]
	global_store_dwordx4 v[168:169], v[190:193], off offset:64
	s_waitcnt vmcnt(4)
	v_pk_fma_f32 v[196:197], v[6:7], v[212:213], v[196:197]
	v_pk_fma_f32 v[194:195], v[4:5], v[210:211], v[194:195]
	global_store_dwordx4 v[168:169], v[194:197], off offset:512
	s_waitcnt vmcnt(3)
	v_pk_fma_f32 v[200:201], v[2:3], v[216:217], v[200:201]
	v_pk_fma_f32 v[198:199], v[0:1], v[214:215], v[198:199]
	global_store_dwordx4 v[168:169], v[198:201], off offset:576
